# attention: second wave group static prio +1, MFMA sections (QK, PV) raised by 2 in both groups
# baseline (speedup 1.0000x reference)
; __device__ __forceinline__ bf16_t f2bf(float f) { return (bf16_t)(pk2(f, 0.f) & 0xffffu); }
; __device__ __forceinline__ int crow(int r, int hi) { return (r & 3) + 8 * (r >> 2) + 4 * hi; }
; __device__ __forceinline__ void attn_phase(const Ctx& c, const Params& p, int o, int first, int cidx) {
;     ...
;         float l; { auto rr = __builtin_amdgcn_permlane32_swap(asu(lrun), asu(lrun), false, false); l = asf(rr[0]) + asf(rr[1]); }
;         const float inv = 1.f / l;
;         bf16_t* yo = Y + (size_t)(b * T_ + qs + l31) * D_ + 512 + h * 64;
; #pragma unroll
;         for (int r = 0; r < 16; ++r) { yo[crow(r, hh)] = f2bf(o0[r] * inv); yo[32 + crow(r, hh)] = f2bf(o1[r] * inv); }
.LBB0_110:
	s_setprio 0
	v_mov_b32_e32 v1, v136
	s_nop 1
	v_permlane32_swap_b32_e32 v136, v1
	v_add_f32_e32 v1, v136, v1
	v_div_scale_f32 v34, s[2:3], v1, v1, 1.0
	v_rcp_f32_e32 v35, v34
	s_lshl_b32 s42, s25, 7
	s_mov_b64 s[2:3], 0x2100400
	v_fma_f32 v36, -v34, v35, 1.0
	v_fmac_f32_e32 v35, v36, v35
	v_div_scale_f32 v36, vcc, 1.0, v1, 1.0
	v_mul_f32_e32 v37, v36, v35
	v_fma_f32 v38, -v34, v37, v36
	v_fmac_f32_e32 v37, v38, v35
	v_fma_f32 v34, -v34, v37, v36
	v_div_fmas_f32 v34, v34, v35, v37
	v_div_fixup_f32 v1, v34, v1, 1.0
	v_lshlrev_b64 v[34:35], 11, v[116:117]
	v_lshl_add_u64 v[34:35], s[22:23], 0, v[34:35]
	v_lshl_add_u64 v[34:35], v[34:35], 0, s[42:43]
	v_mul_f32_e32 v18, v18, v1
	v_lshl_add_u64 v[34:35], v[112:113], 1, v[34:35]
	v_mul_f32_e32 v38, v2, v1
	v_mul_f32_e32 v2, v19, v1
	v_mul_f32_e32 v39, v3, v1
	v_mul_f32_e32 v3, v20, v1
	v_mul_f32_e32 v19, v21, v1
	v_cvt_pk_bf16_f32 v2, v18, v2
	v_add_co_u32_e32 v18, vcc, s36, v34
	v_cvt_pk_bf16_f32 v3, v3, v19
	s_nop 0
	v_addc_co_u32_e32 v19, vcc, 0, v35, vcc
	v_mul_f32_e32 v4, v4, v1
	global_store_dwordx2 v[18:19], v[2:3], off offset:1024
	v_mul_f32_e32 v2, v5, v1
	v_lshl_add_u64 v[36:37], v[34:35], 0, s[2:3]
	v_cvt_pk_bf16_f32 v3, v4, v2
	v_cvt_pk_bf16_f32 v2, v38, v39
	global_store_dwordx2 v[36:37], v[2:3], off offset:64
	v_mul_f32_e32 v2, v22, v1
	v_mul_f32_e32 v4, v6, v1
	v_mul_f32_e32 v5, v23, v1
	v_mul_f32_e32 v6, v7, v1
	v_mul_f32_e32 v3, v24, v1
	v_mul_f32_e32 v7, v8, v1
	v_mul_f32_e32 v8, v25, v1
	v_cvt_pk_bf16_f32 v3, v3, v8
	v_cvt_pk_bf16_f32 v2, v2, v5
	global_store_dwordx2 v[36:37], v[2:3], off offset:16
	v_mul_f32_e32 v2, v9, v1
	v_cvt_pk_bf16_f32 v3, v7, v2
	v_cvt_pk_bf16_f32 v2, v4, v6
	global_store_dwordx2 v[36:37], v[2:3], off offset:80
	v_mul_f32_e32 v2, v26, v1
	v_mul_f32_e32 v5, v27, v1
	v_mul_f32_e32 v3, v28, v1
	v_mul_f32_e32 v8, v29, v1
	v_cvt_pk_bf16_f32 v3, v3, v8
	v_cvt_pk_bf16_f32 v2, v2, v5
	v_mul_f32_e32 v4, v10, v1
	v_mul_f32_e32 v6, v11, v1
	v_mul_f32_e32 v7, v12, v1
	global_store_dwordx2 v[36:37], v[2:3], off offset:32
	v_mul_f32_e32 v2, v13, v1
	v_cvt_pk_bf16_f32 v3, v7, v2
	v_cvt_pk_bf16_f32 v2, v4, v6
	global_store_dwordx2 v[36:37], v[2:3], off offset:96
	v_mul_f32_e32 v2, v30, v1
	v_mul_f32_e32 v5, v31, v1
	v_mul_f32_e32 v3, v32, v1
	v_mul_f32_e32 v8, v33, v1
	v_mul_f32_e32 v4, v14, v1
	v_mul_f32_e32 v6, v15, v1
	v_mul_f32_e32 v7, v16, v1
	v_cvt_pk_bf16_f32 v3, v3, v8
	v_cvt_pk_bf16_f32 v2, v2, v5
	v_mul_f32_e32 v1, v17, v1
	global_store_dwordx2 v[36:37], v[2:3], off offset:48
	v_cvt_pk_bf16_f32 v3, v7, v1
	v_cvt_pk_bf16_f32 v2, v4, v6
	s_mov_b64 s[2:3], 0
	global_store_dwordx2 v[36:37], v[2:3], off offset:112

; #define LAS __attribute__((address_space(3)))
; __device__ __forceinline__ int crow(int r, int hi) { return (r & 3) + 8 * (r >> 2) + 4 * hi; }
; __device__ __forceinline__ void attn_phase(const Ctx& c, const Params& p, int o, int first, int cidx) {
;     ...
;             if (kv0 <= qs + 31) {
;                 const LAS bf16_t* kb = sK + buf * 6656 + l31 * 104 + 8 * hh; const LAS bf16_t* vb = sVt + buf * 4608 + l31 * 72 + 4 * hh;
;                 f32x16 p0 = {}, p1 = {};
; #pragma unroll
;                 for (int ks = 0; ks < 6; ++ks) { const bf16x8 k0 = *(const LAS bf16x8*)(kb + 16 * ks); const bf16x8 k1 = *(const LAS bf16x8*)(kb + 32 * 104 + 16 * ks);
;                     p0 = __builtin_amdgcn_mfma_f32_32x32x16_bf16(k0, qf[ks], p0, 0, 0, 0); p1 = __builtin_amdgcn_mfma_f32_32x32x16_bf16(k1, qf[ks], p1, 0, 0, 0); }
;                 if (kv0 + 63 > qs) { const int q = qs + l31;
; #pragma unroll
;                     for (int r = 0; r < 16; ++r) { const int kv = kv0 + crow(r, hh); if (kv > q) p0[r] = -INFINITY; if (kv + 32 > q) p1[r] = -INFINITY; } }
.LBB0_124:
	s_and_b32 s18, s10, 1
	s_cmp_gt_i32 s42, s29
	s_cbranch_scc1 .LBB0_130
	s_mul_i32 s10, s18, 0x3400
	s_mul_i32 s11, s18, 0x2400
	v_add_u32_e32 v1, s10, v130
	v_add_u32_e32 v142, s11, v131
	ds_read_b128 v[200:203], v1
	ds_read_b128 v[204:207], v1 offset:6656
	ds_read_b128 v[208:211], v1 offset:32
	ds_read_b128 v[212:215], v1 offset:6688
	ds_read_b128 v[216:219], v1 offset:64
	ds_read_b128 v[220:223], v1 offset:6720
	ds_read_b128 v[224:227], v1 offset:96
	ds_read_b128 v[228:231], v1 offset:6752
	ds_read_b128 v[232:235], v1 offset:128
	ds_read_b128 v[236:239], v1 offset:6784
	ds_read_b128 v[240:243], v1 offset:160
	ds_read_b128 v[244:247], v1 offset:6816
	v_add_u32_e32 v143, 0x7a00, v142
	v_add_u32_e32 v142, 0x6800, v142
	s_add_i32 s10, s42, 63
	s_cmp_le_i32 s10, s26
	s_waitcnt lgkmcnt(10)
	s_setprio 2
	v_mfma_f32_32x32x16_bf16 v[50:65], v[200:203], v[66:69], 0
	v_mfma_f32_32x32x16_bf16 v[34:49], v[204:207], v[66:69], 0
	s_waitcnt lgkmcnt(8)
	v_mfma_f32_32x32x16_bf16 v[50:65], v[208:211], v[70:73], v[50:65]
	v_mfma_f32_32x32x16_bf16 v[34:49], v[212:215], v[70:73], v[34:49]
	s_waitcnt lgkmcnt(6)
	v_mfma_f32_32x32x16_bf16 v[50:65], v[216:219], v[74:77], v[50:65]
	v_mfma_f32_32x32x16_bf16 v[34:49], v[220:223], v[74:77], v[34:49]
	ds_read_b64 v[200:201], v142
	ds_read_b64 v[202:203], v142 offset:16
	ds_read_b64 v[204:205], v142 offset:32
	ds_read_b64 v[206:207], v142 offset:48
	s_waitcnt lgkmcnt(8)
	v_mfma_f32_32x32x16_bf16 v[50:65], v[224:227], v[78:81], v[50:65]
	v_mfma_f32_32x32x16_bf16 v[34:49], v[228:231], v[78:81], v[34:49]
	ds_read_b64 v[208:209], v142 offset:64
	ds_read_b64 v[210:211], v142 offset:80
	ds_read_b64 v[212:213], v142 offset:96
	ds_read_b64 v[214:215], v142 offset:112
	s_waitcnt lgkmcnt(10)
	v_mfma_f32_32x32x16_bf16 v[50:65], v[232:235], v[82:85], v[50:65]
	v_mfma_f32_32x32x16_bf16 v[34:49], v[236:239], v[82:85], v[34:49]
	ds_read_b64 v[216:217], v143
	ds_read_b64 v[218:219], v143 offset:16
	ds_read_b64 v[220:221], v143 offset:32
	ds_read_b64 v[222:223], v143 offset:48
	s_waitcnt lgkmcnt(12)
	v_mfma_f32_32x32x16_bf16 v[50:65], v[240:243], v[86:89], v[50:65]
	v_mfma_f32_32x32x16_bf16 v[34:49], v[244:247], v[86:89], v[34:49]
	s_setprio 0
	ds_read_b64 v[224:225], v143 offset:64
	ds_read_b64 v[226:227], v143 offset:80
	ds_read_b64 v[228:229], v143 offset:96
	s_waitcnt lgkmcnt(7)
	ds_read_b64 v[230:231], v143 offset:112
	s_cbranch_scc1 .LBB0_127
	v_add_u32_e32 v1, s42, v112
	v_add_u32_e32 v138, 32, v1
	v_cmp_le_i32_e32 vcc, v138, v135
	v_add_u32_e32 v138, 33, v1
	s_nop 6
	v_cndmask_b32_e32 v34, v173, v34, vcc
	v_cmp_lt_i32_e32 vcc, v1, v135
	s_nop 1
	v_cndmask_b32_e32 v51, v173, v51, vcc
	v_cmp_le_i32_e32 vcc, v1, v135
	s_nop 1
	v_cndmask_b32_e32 v50, v173, v50, vcc
	v_cmp_le_i32_e32 vcc, v138, v135
	v_add_u32_e32 v138, 2, v1
	s_nop 0
	v_cndmask_b32_e32 v35, v173, v35, vcc
	v_cmp_le_i32_e32 vcc, v138, v135
	v_add_u32_e32 v138, 34, v1
	s_nop 0
	v_cndmask_b32_e32 v52, v173, v52, vcc
	v_cmp_le_i32_e32 vcc, v138, v135
	v_add_u32_e32 v138, 3, v1
	s_nop 0
	v_cndmask_b32_e32 v36, v173, v36, vcc
	v_cmp_le_i32_e32 vcc, v138, v135
	v_add_u32_e32 v138, 35, v1
	s_nop 0
	v_cndmask_b32_e32 v53, v173, v53, vcc
	v_cmp_le_i32_e32 vcc, v138, v135
	v_add_u32_e32 v138, 8, v1
	s_nop 0
	v_cndmask_b32_e32 v37, v173, v37, vcc
	v_cmp_le_i32_e32 vcc, v138, v135
	v_add_u32_e32 v138, 40, v1
	s_nop 0
	v_cndmask_b32_e32 v54, v173, v54, vcc
	v_cmp_le_i32_e32 vcc, v138, v135
	v_add_u32_e32 v138, 9, v1
	s_nop 0
	v_cndmask_b32_e32 v38, v173, v38, vcc
	v_cmp_le_i32_e32 vcc, v138, v135
	v_add_u32_e32 v138, 41, v1
	s_nop 0
	v_cndmask_b32_e32 v55, v173, v55, vcc
	v_cmp_le_i32_e32 vcc, v138, v135
	v_add_u32_e32 v138, 10, v1
	s_nop 0
	v_cndmask_b32_e32 v39, v173, v39, vcc
	v_cmp_le_i32_e32 vcc, v138, v135
	v_add_u32_e32 v138, 42, v1
	s_nop 0
	v_cndmask_b32_e32 v56, v173, v56, vcc
	v_cmp_le_i32_e32 vcc, v138, v135
	v_add_u32_e32 v138, 11, v1
	s_nop 0
	v_cndmask_b32_e32 v40, v173, v40, vcc
	v_cmp_le_i32_e32 vcc, v138, v135
	v_add_u32_e32 v138, 43, v1
	s_nop 0
	v_cndmask_b32_e32 v57, v173, v57, vcc
	v_cmp_le_i32_e32 vcc, v138, v135
	v_add_u32_e32 v138, 16, v1
	s_nop 0
	v_cndmask_b32_e32 v41, v173, v41, vcc
	v_cmp_le_i32_e32 vcc, v138, v135
	v_add_u32_e32 v138, 48, v1
	s_nop 0
	v_cndmask_b32_e32 v58, v173, v58, vcc
	v_cmp_le_i32_e32 vcc, v138, v135
	v_add_u32_e32 v138, 17, v1
	s_nop 0
	v_cndmask_b32_e32 v42, v173, v42, vcc
	v_cmp_le_i32_e32 vcc, v138, v135
	v_add_u32_e32 v138, 49, v1
	s_nop 0
	v_cndmask_b32_e32 v59, v173, v59, vcc
	v_cmp_le_i32_e32 vcc, v138, v135
	v_add_u32_e32 v138, 18, v1
	s_nop 0
	v_cndmask_b32_e32 v43, v173, v43, vcc
	v_cmp_le_i32_e32 vcc, v138, v135
	v_add_u32_e32 v138, 50, v1
	s_nop 0
	v_cndmask_b32_e32 v60, v173, v60, vcc
	v_cmp_le_i32_e32 vcc, v138, v135
	v_add_u32_e32 v138, 19, v1
	s_nop 0
	v_cndmask_b32_e32 v44, v173, v44, vcc
	v_cmp_le_i32_e32 vcc, v138, v135
	v_add_u32_e32 v138, 51, v1
	s_nop 0
	v_cndmask_b32_e32 v61, v173, v61, vcc
	v_cmp_le_i32_e32 vcc, v138, v135
	v_add_u32_e32 v138, 24, v1
	s_nop 0
	v_cndmask_b32_e32 v45, v173, v45, vcc
	v_cmp_le_i32_e32 vcc, v138, v135
	v_add_u32_e32 v138, 56, v1
	s_nop 0
	v_cndmask_b32_e32 v62, v173, v62, vcc
	v_cmp_le_i32_e32 vcc, v138, v135
	v_add_u32_e32 v138, 25, v1
	s_nop 0
	v_cndmask_b32_e32 v46, v173, v46, vcc
	v_cmp_le_i32_e32 vcc, v138, v135
	v_add_u32_e32 v138, 57, v1
	s_nop 0
	v_cndmask_b32_e32 v63, v173, v63, vcc
	v_cmp_le_i32_e32 vcc, v138, v135
	v_add_u32_e32 v138, 26, v1
	s_nop 0
	v_cndmask_b32_e32 v47, v173, v47, vcc
	v_cmp_le_i32_e32 vcc, v138, v135
	v_add_u32_e32 v138, 58, v1
	s_nop 0
	v_cndmask_b32_e32 v64, v173, v64, vcc
	v_cmp_le_i32_e32 vcc, v138, v135
	v_add_u32_e32 v138, 27, v1
	v_add_u32_e32 v1, 59, v1
	v_cndmask_b32_e32 v48, v173, v48, vcc
	v_cmp_le_i32_e32 vcc, v138, v135
	s_nop 1
	v_cndmask_b32_e32 v65, v173, v65, vcc
	v_cmp_le_i32_e32 vcc, v1, v135
	s_nop 1
	v_cndmask_b32_e32 v49, v173, v49, vcc

; #define PV_STEP(OACC, mm, ktt, ss, PF) do { OACC = __builtin_amdgcn_mfma_f32_32x32x16_bf16(ldA_perm(vb + (mm) * 32 * 72 + 32 * (ktt) + 16 * (ss)), PF, OACC, 0, 0, 0); } while (0)
; __device__ __forceinline__ void attn_phase(const Ctx& c, const Params& p, int o, int first, int cidx) {
;     ...
;                 const float mnew = fmaxf(mrun, mx);
;                 if (__any(mnew > mrun)) { const float alpha = __builtin_amdgcn_exp2f(mrun - mnew); lrun *= alpha; o0 = o0 * alpha; o1 = o1 * alpha; }
;                 mrun = mnew;
;                 f32x16 e0, e1;
; #pragma unroll
;                 for (int r = 0; r < 16; ++r) { e0[r] = __builtin_amdgcn_exp2f(p0[r] - mnew); e1[r] = __builtin_amdgcn_exp2f(p1[r] - mnew); }
;                 p0 = e0; p1 = e1;
;                 { const f32x16 t = e0 + e1; lrun += ((t[0] + t[1]) + (t[2] + t[3])) + ((t[4] + t[5]) + (t[6] + t[7])) + ((t[8] + t[9]) + (t[10] + t[11])) + ((t[12] + t[13]) + (t[14] + t[15])); }
;                 const bf16x8 pf00 = pkfrag(p0, 0), pf01 = pkfrag(p0, 1), pf10 = pkfrag(p1, 0), pf11 = pkfrag(p1, 1);
;     ...
;                 PV_STEP(o0, 0, 0, 0, pf00); PV_STEP(o0, 0, 0, 1, pf01); PV_STEP(o0, 0, 1, 0, pf10); PV_STEP(o0, 0, 1, 1, pf11);
;                 PV_STEP(o1, 1, 0, 0, pf00); PV_STEP(o1, 1, 0, 1, pf01); PV_STEP(o1, 1, 1, 0, pf10); PV_STEP(o1, 1, 1, 1, pf11);
.LBB0_129:
	v_sub_f32_e32 v38, v38, v1
	v_exp_f32_e32 v138, v38
	v_sub_f32_e32 v38, v55, v1
	v_exp_f32_e32 v55, v38
	v_sub_f32_e32 v38, v39, v1
	v_sub_f32_e32 v39, v40, v1
	v_sub_f32_e32 v40, v41, v1
	v_sub_f32_e32 v41, v42, v1
	v_sub_f32_e32 v42, v43, v1
	v_exp_f32_e32 v139, v38
	v_sub_f32_e32 v38, v56, v1
	v_exp_f32_e32 v56, v39
	v_sub_f32_e32 v39, v57, v1
	v_exp_f32_e32 v57, v40
	v_sub_f32_e32 v40, v58, v1
	v_exp_f32_e32 v58, v41
	v_sub_f32_e32 v41, v59, v1
	v_exp_f32_e32 v59, v42
	v_sub_f32_e32 v42, v60, v1
	v_exp_f32_e32 v60, v42
	v_sub_f32_e32 v42, v44, v1
	v_exp_f32_e32 v140, v42
	v_sub_f32_e32 v42, v61, v1
	v_exp_f32_e32 v61, v42
	v_sub_f32_e32 v42, v45, v1
	v_exp_f32_e32 v141, v42
	v_sub_f32_e32 v42, v62, v1
	v_exp_f32_e32 v44, v42
	v_sub_f32_e32 v42, v46, v1
	v_exp_f32_e32 v62, v42
	v_sub_f32_e32 v42, v63, v1
	v_sub_f32_e32 v50, v50, v1
	v_sub_f32_e32 v34, v34, v1
	v_sub_f32_e32 v51, v51, v1
	v_sub_f32_e32 v35, v35, v1
	v_sub_f32_e32 v52, v52, v1
	v_sub_f32_e32 v36, v36, v1
	v_sub_f32_e32 v53, v53, v1
	v_sub_f32_e32 v37, v37, v1
	v_exp_f32_e32 v45, v42
	v_sub_f32_e32 v42, v47, v1
	v_exp_f32_e32 v50, v50
	v_exp_f32_e32 v34, v34
	v_exp_f32_e32 v51, v51
	v_exp_f32_e32 v35, v35
	v_exp_f32_e32 v52, v52
	v_exp_f32_e32 v36, v36
	v_exp_f32_e32 v53, v53
	v_exp_f32_e32 v37, v37
	v_sub_f32_e32 v54, v54, v1
	v_exp_f32_e32 v63, v42
	v_sub_f32_e32 v42, v64, v1
	v_exp_f32_e32 v54, v54
	v_exp_f32_e32 v38, v38
	v_exp_f32_e32 v39, v39
	v_exp_f32_e32 v64, v42
	v_sub_f32_e32 v42, v48, v1
	v_exp_f32_e32 v142, v42
	v_sub_f32_e32 v42, v65, v1
	v_exp_f32_e32 v65, v42
	v_sub_f32_e32 v42, v49, v1
	v_exp_f32_e32 v40, v40
	v_exp_f32_e32 v41, v41
	v_exp_f32_e32 v143, v42
	v_pk_add_f32 v[184:185], v[52:53], v[36:37]
	v_pk_add_f32 v[186:187], v[50:51], v[34:35]
	v_pk_add_f32 v[170:171], v[38:39], v[56:57]
	v_pk_add_f32 v[174:175], v[54:55], v[138:139]
	v_pk_mov_b32 v[188:189], v[186:187], v[184:185] op_sel:[1,0]
	v_mov_b32_e32 v187, v185
	v_pk_add_f32 v[184:185], v[188:189], v[186:187]
	v_pk_mov_b32 v[186:187], v[174:175], v[170:171] op_sel:[1,0]
	v_mov_b32_e32 v175, v171
	v_pk_add_f32 v[170:171], v[186:187], v[174:175]
	v_pk_add_f32 v[42:43], v[64:65], v[142:143]
	v_pk_add_f32 v[46:47], v[44:45], v[62:63]
	v_pk_add_f32 v[48:49], v[60:61], v[140:141]
	v_pk_add_f32 v[168:169], v[40:41], v[58:59]
	v_pk_add_f32 v[184:185], v[184:185], v[184:185] op_sel_hi:[0,1]
	v_pk_add_f32 v[170:171], v[170:171], v[170:171] op_sel_hi:[0,1]
	v_add_f32_e32 v169, v168, v169
	v_add_f32_e32 v49, v48, v49
	v_mov_b32_e32 v168, v46
	v_mov_b32_e32 v48, v47
	v_mov_b32_e32 v184, v42
	v_mov_b32_e32 v170, v43
	s_mul_i32 s10, s18, 0x2400
	v_pk_add_f32 v[46:47], v[168:169], v[48:49]
	v_pk_add_f32 v[42:43], v[184:185], v[170:171]
	v_cvt_pk_bf16_f32 v49, v38, v39
	v_pk_add_f32 v[42:43], v[46:47], v[42:43]
	v_cvt_pk_bf16_f32 v38, v34, v35
	v_cvt_pk_bf16_f32 v34, v58, v59
	v_add_u32_e32 v58, s10, v131
	v_add_f32_e32 v42, v42, v43
	v_add_u32_e32 v59, 0x6800, v58
	v_add_f32_e32 v136, v42, v136
	v_cvt_pk_bf16_f32 v46, v50, v51
	v_cvt_pk_bf16_f32 v47, v52, v53
	v_cvt_pk_bf16_f32 v48, v54, v55
	v_cvt_pk_bf16_f32 v42, v40, v41
	v_cvt_pk_bf16_f32 v41, v56, v57
	s_waitcnt lgkmcnt(0)
	s_setprio 2
	v_mfma_f32_32x32x16_bf16 v[18:33], v[200:203], v[46:49], v[18:33]
	v_cvt_pk_bf16_f32 v43, v60, v61
	v_cvt_pk_bf16_f32 v44, v44, v45
	v_cvt_pk_bf16_f32 v45, v64, v65
	v_cvt_pk_bf16_f32 v39, v36, v37
	v_cvt_pk_bf16_f32 v40, v138, v139
	v_cvt_pk_bf16_f32 v35, v140, v141
	v_cvt_pk_bf16_f32 v36, v62, v63
	v_cvt_pk_bf16_f32 v37, v142, v143
	v_mfma_f32_32x32x16_bf16 v[2:17], v[216:219], v[46:49], v[2:17]
	v_mfma_f32_32x32x16_bf16 v[18:33], v[204:207], v[42:45], v[18:33]
	v_mfma_f32_32x32x16_bf16 v[2:17], v[220:223], v[42:45], v[2:17]
	v_mfma_f32_32x32x16_bf16 v[18:33], v[208:211], v[38:41], v[18:33]
	v_mfma_f32_32x32x16_bf16 v[2:17], v[224:227], v[38:41], v[2:17]
	v_mfma_f32_32x32x16_bf16 v[18:33], v[212:215], v[34:37], v[18:33]
	v_mfma_f32_32x32x16_bf16 v[2:17], v[228:231], v[34:37], v[2:17]
	s_setprio 0
	s_andn2_b64 vcc, exec, s[2:3]
	s_cbranch_vccz .LBB0_131
	s_branch .LBB0_134

; #define PV_STEP(OACC, mm, ktt, ss, PF) do { OACC = __builtin_amdgcn_mfma_f32_32x32x16_bf16(ldA_perm(vb + (mm) * 32 * 72 + 32 * (ktt) + 16 * (ss)), PF, OACC, 0, 0, 0); } while (0)
; __device__ __forceinline__ void attn_phase(const Ctx& c, const Params& p, int o, int first, int cidx) {
;     ...
;                 const float mnew = fmaxf(mrun, mx);
;                 if (__any(mnew > mrun)) { const float alpha = __builtin_amdgcn_exp2f(mrun - mnew); lrun *= alpha; o0 = o0 * alpha; o1 = o1 * alpha; }
;                 mrun = mnew;
;                 f32x16 e0, e1;
; #pragma unroll
;                 for (int r = 0; r < 16; ++r) { e0[r] = __builtin_amdgcn_exp2f(p0[r] - mnew); e1[r] = __builtin_amdgcn_exp2f(p1[r] - mnew); }
;                 p0 = e0; p1 = e1;
;                 { const f32x16 t = e0 + e1; lrun += ((t[0] + t[1]) + (t[2] + t[3])) + ((t[4] + t[5]) + (t[6] + t[7])) + ((t[8] + t[9]) + (t[10] + t[11])) + ((t[12] + t[13]) + (t[14] + t[15])); }
;                 const bf16x8 pf00 = pkfrag(p0, 0), pf01 = pkfrag(p0, 1), pf10 = pkfrag(p1, 0), pf11 = pkfrag(p1, 1);
;     ...
;                 PV_STEP(o0, 0, 0, 0, pf00); PV_STEP(o0, 0, 0, 1, pf01); PV_STEP(o0, 0, 1, 0, pf10); PV_STEP(o0, 0, 1, 1, pf11);
;                 PV_STEP(o1, 1, 0, 0, pf00); PV_STEP(o1, 1, 0, 1, pf01); PV_STEP(o1, 1, 1, 0, pf10); PV_STEP(o1, 1, 1, 1, pf11);
.Lsb_129:
	v_sub_f32_e32 v38, v38, v1
	v_exp_f32_e32 v138, v38
	v_sub_f32_e32 v38, v55, v1
	v_exp_f32_e32 v55, v38
	v_sub_f32_e32 v38, v39, v1
	v_sub_f32_e32 v39, v40, v1
	v_sub_f32_e32 v40, v41, v1
	v_sub_f32_e32 v41, v42, v1
	v_sub_f32_e32 v42, v43, v1
	v_exp_f32_e32 v139, v38
	v_sub_f32_e32 v38, v56, v1
	v_exp_f32_e32 v56, v39
	v_sub_f32_e32 v39, v57, v1
	v_exp_f32_e32 v57, v40
	v_sub_f32_e32 v40, v58, v1
	v_exp_f32_e32 v58, v41
	v_sub_f32_e32 v41, v59, v1
	v_exp_f32_e32 v59, v42
	v_sub_f32_e32 v42, v60, v1
	v_exp_f32_e32 v60, v42
	v_sub_f32_e32 v42, v44, v1
	v_exp_f32_e32 v140, v42
	v_sub_f32_e32 v42, v61, v1
	v_exp_f32_e32 v61, v42
	v_sub_f32_e32 v42, v45, v1
	v_exp_f32_e32 v141, v42
	v_sub_f32_e32 v42, v62, v1
	v_exp_f32_e32 v44, v42
	v_sub_f32_e32 v42, v46, v1
	v_exp_f32_e32 v62, v42
	v_sub_f32_e32 v42, v63, v1
	v_sub_f32_e32 v50, v50, v1
	v_sub_f32_e32 v34, v34, v1
	v_sub_f32_e32 v51, v51, v1
	v_sub_f32_e32 v35, v35, v1
	v_sub_f32_e32 v52, v52, v1
	v_sub_f32_e32 v36, v36, v1
	v_sub_f32_e32 v53, v53, v1
	v_sub_f32_e32 v37, v37, v1
	v_exp_f32_e32 v45, v42
	v_sub_f32_e32 v42, v47, v1
	v_exp_f32_e32 v50, v50
	v_exp_f32_e32 v34, v34
	v_exp_f32_e32 v51, v51
	v_exp_f32_e32 v35, v35
	v_exp_f32_e32 v52, v52
	v_exp_f32_e32 v36, v36
	v_exp_f32_e32 v53, v53
	v_exp_f32_e32 v37, v37
	v_sub_f32_e32 v54, v54, v1
	v_exp_f32_e32 v63, v42
	v_sub_f32_e32 v42, v64, v1
	v_exp_f32_e32 v54, v54
	v_exp_f32_e32 v38, v38
	v_exp_f32_e32 v39, v39
	v_exp_f32_e32 v64, v42
	v_sub_f32_e32 v42, v48, v1
	v_exp_f32_e32 v142, v42
	v_sub_f32_e32 v42, v65, v1
	v_exp_f32_e32 v65, v42
	v_sub_f32_e32 v42, v49, v1
	v_exp_f32_e32 v40, v40
	v_exp_f32_e32 v41, v41
	v_exp_f32_e32 v143, v42
	v_pk_add_f32 v[184:185], v[52:53], v[36:37]
	v_pk_add_f32 v[186:187], v[50:51], v[34:35]
	v_pk_add_f32 v[170:171], v[38:39], v[56:57]
	v_pk_add_f32 v[174:175], v[54:55], v[138:139]
	v_pk_mov_b32 v[188:189], v[186:187], v[184:185] op_sel:[1,0]
	v_mov_b32_e32 v187, v185
	v_pk_add_f32 v[184:185], v[188:189], v[186:187]
	v_pk_mov_b32 v[186:187], v[174:175], v[170:171] op_sel:[1,0]
	v_mov_b32_e32 v175, v171
	v_pk_add_f32 v[170:171], v[186:187], v[174:175]
	v_pk_add_f32 v[42:43], v[64:65], v[142:143]
	v_pk_add_f32 v[46:47], v[44:45], v[62:63]
	v_pk_add_f32 v[48:49], v[60:61], v[140:141]
	v_pk_add_f32 v[168:169], v[40:41], v[58:59]
	v_pk_add_f32 v[184:185], v[184:185], v[184:185] op_sel_hi:[0,1]
	v_pk_add_f32 v[170:171], v[170:171], v[170:171] op_sel_hi:[0,1]
	v_add_f32_e32 v169, v168, v169
	v_add_f32_e32 v49, v48, v49
	v_mov_b32_e32 v168, v46
	v_mov_b32_e32 v48, v47
	v_mov_b32_e32 v184, v42
	v_mov_b32_e32 v170, v43
	s_mul_i32 s10, s18, 0x2400
	v_pk_add_f32 v[46:47], v[168:169], v[48:49]
	v_pk_add_f32 v[42:43], v[184:185], v[170:171]
	v_cvt_pk_bf16_f32 v49, v38, v39
	v_pk_add_f32 v[42:43], v[46:47], v[42:43]
	v_cvt_pk_bf16_f32 v38, v34, v35
	v_cvt_pk_bf16_f32 v34, v58, v59
	v_add_u32_e32 v58, s10, v131
	v_add_f32_e32 v42, v42, v43
	v_add_u32_e32 v59, 0x6800, v58
	v_add_f32_e32 v136, v42, v136
	v_cvt_pk_bf16_f32 v46, v50, v51
	v_cvt_pk_bf16_f32 v47, v52, v53
	v_cvt_pk_bf16_f32 v48, v54, v55
	v_cvt_pk_bf16_f32 v42, v40, v41
	v_cvt_pk_bf16_f32 v41, v56, v57
	s_waitcnt lgkmcnt(0)
	s_setprio 3
	v_mfma_f32_32x32x16_bf16 v[18:33], v[200:203], v[46:49], v[18:33]
	v_cvt_pk_bf16_f32 v43, v60, v61
	v_cvt_pk_bf16_f32 v44, v44, v45
	v_cvt_pk_bf16_f32 v45, v64, v65
	v_cvt_pk_bf16_f32 v39, v36, v37
	v_cvt_pk_bf16_f32 v40, v138, v139
	v_cvt_pk_bf16_f32 v35, v140, v141
	v_cvt_pk_bf16_f32 v36, v62, v63
	v_cvt_pk_bf16_f32 v37, v142, v143
	v_mfma_f32_32x32x16_bf16 v[2:17], v[216:219], v[46:49], v[2:17]
	v_mfma_f32_32x32x16_bf16 v[18:33], v[204:207], v[42:45], v[18:33]
	v_mfma_f32_32x32x16_bf16 v[2:17], v[220:223], v[42:45], v[2:17]
	v_mfma_f32_32x32x16_bf16 v[18:33], v[208:211], v[38:41], v[18:33]
	v_mfma_f32_32x32x16_bf16 v[2:17], v[224:227], v[38:41], v[2:17]
	v_mfma_f32_32x32x16_bf16 v[18:33], v[212:215], v[34:37], v[18:33]
	v_mfma_f32_32x32x16_bf16 v[2:17], v[228:231], v[34:37], v[2:17]
	s_setprio 1
	v_mov_b32_e32 v137, v1
; #define LAS __attribute__((address_space(3)))
; __device__ __forceinline__ int crow(int r, int hi) { return (r & 3) + 8 * (r >> 2) + 4 * hi; }
; __device__ __forceinline__ void attn_phase(const Ctx& c, const Params& p, int o, int first, int cidx) {
;     ...
;             if (kv0 <= qs + 31) {
;                 const LAS bf16_t* kb = sK + buf * 6656 + l31 * 104 + 8 * hh; const LAS bf16_t* vb = sVt + buf * 4608 + l31 * 72 + 4 * hh;
;                 f32x16 p0 = {}, p1 = {};
; #pragma unroll
;                 for (int ks = 0; ks < 6; ++ks) { const bf16x8 k0 = *(const LAS bf16x8*)(kb + 16 * ks); const bf16x8 k1 = *(const LAS bf16x8*)(kb + 32 * 104 + 16 * ks);
;                     p0 = __builtin_amdgcn_mfma_f32_32x32x16_bf16(k0, qf[ks], p0, 0, 0, 0); p1 = __builtin_amdgcn_mfma_f32_32x32x16_bf16(k1, qf[ks], p1, 0, 0, 0); }
;                 if (kv0 + 63 > qs) { const int q = qs + l31;
; #pragma unroll
;                     for (int r = 0; r < 16; ++r) { const int kv = kv0 + crow(r, hh); if (kv > q) p0[r] = -INFINITY; if (kv + 32 > q) p1[r] = -INFINITY; } }
.Lsb_nosm:
	s_cmp_gt_i32 s42, s29
	s_cbranch_scc1 .Lsb_noqk
	s_mul_i32 s10, s18, 0x3400
	s_mul_i32 s11, s18, 0x2400
	v_add_u32_e32 v1, s10, v130
	v_add_u32_e32 v142, s11, v131
	ds_read_b128 v[200:203], v1
	ds_read_b128 v[204:207], v1 offset:6656
	ds_read_b128 v[208:211], v1 offset:32
	ds_read_b128 v[212:215], v1 offset:6688
	ds_read_b128 v[216:219], v1 offset:64
	ds_read_b128 v[220:223], v1 offset:6720
	ds_read_b128 v[224:227], v1 offset:96
	ds_read_b128 v[228:231], v1 offset:6752
	ds_read_b128 v[232:235], v1 offset:128
	ds_read_b128 v[236:239], v1 offset:6784
	ds_read_b128 v[240:243], v1 offset:160
	ds_read_b128 v[244:247], v1 offset:6816
	v_add_u32_e32 v143, 0x7a00, v142
	v_add_u32_e32 v142, 0x6800, v142
	s_add_i32 s10, s42, 63
	s_cmp_le_i32 s10, s26
	s_waitcnt lgkmcnt(10)
	s_setprio 3
	v_mfma_f32_32x32x16_bf16 v[50:65], v[200:203], v[66:69], 0
	v_mfma_f32_32x32x16_bf16 v[34:49], v[204:207], v[66:69], 0
	s_waitcnt lgkmcnt(8)
	v_mfma_f32_32x32x16_bf16 v[50:65], v[208:211], v[70:73], v[50:65]
	v_mfma_f32_32x32x16_bf16 v[34:49], v[212:215], v[70:73], v[34:49]
	s_waitcnt lgkmcnt(6)
	v_mfma_f32_32x32x16_bf16 v[50:65], v[216:219], v[74:77], v[50:65]
	v_mfma_f32_32x32x16_bf16 v[34:49], v[220:223], v[74:77], v[34:49]
	ds_read_b64 v[200:201], v142
	ds_read_b64 v[202:203], v142 offset:16
	ds_read_b64 v[204:205], v142 offset:32
	ds_read_b64 v[206:207], v142 offset:48
	s_waitcnt lgkmcnt(8)
	v_mfma_f32_32x32x16_bf16 v[50:65], v[224:227], v[78:81], v[50:65]
	v_mfma_f32_32x32x16_bf16 v[34:49], v[228:231], v[78:81], v[34:49]
	ds_read_b64 v[208:209], v142 offset:64
	ds_read_b64 v[210:211], v142 offset:80
	ds_read_b64 v[212:213], v142 offset:96
	ds_read_b64 v[214:215], v142 offset:112
	s_waitcnt lgkmcnt(10)
	v_mfma_f32_32x32x16_bf16 v[50:65], v[232:235], v[82:85], v[50:65]
	v_mfma_f32_32x32x16_bf16 v[34:49], v[236:239], v[82:85], v[34:49]
	ds_read_b64 v[216:217], v143
	ds_read_b64 v[218:219], v143 offset:16
	ds_read_b64 v[220:221], v143 offset:32
	ds_read_b64 v[222:223], v143 offset:48
	s_waitcnt lgkmcnt(12)
	v_mfma_f32_32x32x16_bf16 v[50:65], v[240:243], v[86:89], v[50:65]
	v_mfma_f32_32x32x16_bf16 v[34:49], v[244:247], v[86:89], v[34:49]
	s_setprio 1
	ds_read_b64 v[224:225], v143 offset:64
	ds_read_b64 v[226:227], v143 offset:80
	ds_read_b64 v[228:229], v143 offset:96
	s_waitcnt lgkmcnt(7)
	ds_read_b64 v[230:231], v143 offset:112
	s_cbranch_scc1 .Lsb_nomask
	v_add_u32_e32 v1, s42, v112
	v_add_u32_e32 v138, 32, v1
	v_cmp_le_i32_e32 vcc, v138, v135
	v_add_u32_e32 v138, 33, v1
	s_nop 6
	v_cndmask_b32_e32 v34, v173, v34, vcc
	v_cmp_lt_i32_e32 vcc, v1, v135
	s_nop 1
	v_cndmask_b32_e32 v51, v173, v51, vcc
	v_cmp_le_i32_e32 vcc, v1, v135
	s_nop 1
	v_cndmask_b32_e32 v50, v173, v50, vcc
	v_cmp_le_i32_e32 vcc, v138, v135
	v_add_u32_e32 v138, 2, v1
	s_nop 0
	v_cndmask_b32_e32 v35, v173, v35, vcc
	v_cmp_le_i32_e32 vcc, v138, v135
	v_add_u32_e32 v138, 34, v1
	s_nop 0
	v_cndmask_b32_e32 v52, v173, v52, vcc
	v_cmp_le_i32_e32 vcc, v138, v135
	v_add_u32_e32 v138, 3, v1
	s_nop 0
	v_cndmask_b32_e32 v36, v173, v36, vcc
	v_cmp_le_i32_e32 vcc, v138, v135
	v_add_u32_e32 v138, 35, v1
	s_nop 0
	v_cndmask_b32_e32 v53, v173, v53, vcc
	v_cmp_le_i32_e32 vcc, v138, v135
	v_add_u32_e32 v138, 8, v1
	s_nop 0
	v_cndmask_b32_e32 v37, v173, v37, vcc
	v_cmp_le_i32_e32 vcc, v138, v135
	v_add_u32_e32 v138, 40, v1
	s_nop 0
	v_cndmask_b32_e32 v54, v173, v54, vcc
	v_cmp_le_i32_e32 vcc, v138, v135
	v_add_u32_e32 v138, 9, v1
	s_nop 0
	v_cndmask_b32_e32 v38, v173, v38, vcc
	v_cmp_le_i32_e32 vcc, v138, v135
	v_add_u32_e32 v138, 41, v1
	s_nop 0
	v_cndmask_b32_e32 v55, v173, v55, vcc
	v_cmp_le_i32_e32 vcc, v138, v135
	v_add_u32_e32 v138, 10, v1
	s_nop 0
	v_cndmask_b32_e32 v39, v173, v39, vcc
	v_cmp_le_i32_e32 vcc, v138, v135
	v_add_u32_e32 v138, 42, v1
	s_nop 0
	v_cndmask_b32_e32 v56, v173, v56, vcc
	v_cmp_le_i32_e32 vcc, v138, v135
	v_add_u32_e32 v138, 11, v1
	s_nop 0
	v_cndmask_b32_e32 v40, v173, v40, vcc
	v_cmp_le_i32_e32 vcc, v138, v135
	v_add_u32_e32 v138, 43, v1
	s_nop 0
	v_cndmask_b32_e32 v57, v173, v57, vcc
	v_cmp_le_i32_e32 vcc, v138, v135
	v_add_u32_e32 v138, 16, v1
	s_nop 0
	v_cndmask_b32_e32 v41, v173, v41, vcc
	v_cmp_le_i32_e32 vcc, v138, v135
	v_add_u32_e32 v138, 48, v1
	s_nop 0
	v_cndmask_b32_e32 v58, v173, v58, vcc
	v_cmp_le_i32_e32 vcc, v138, v135
	v_add_u32_e32 v138, 17, v1
	s_nop 0
	v_cndmask_b32_e32 v42, v173, v42, vcc
	v_cmp_le_i32_e32 vcc, v138, v135
	v_add_u32_e32 v138, 49, v1
	s_nop 0
	v_cndmask_b32_e32 v59, v173, v59, vcc
	v_cmp_le_i32_e32 vcc, v138, v135
	v_add_u32_e32 v138, 18, v1
	s_nop 0
	v_cndmask_b32_e32 v43, v173, v43, vcc
	v_cmp_le_i32_e32 vcc, v138, v135
	v_add_u32_e32 v138, 50, v1
	s_nop 0
	v_cndmask_b32_e32 v60, v173, v60, vcc
	v_cmp_le_i32_e32 vcc, v138, v135
	v_add_u32_e32 v138, 19, v1
	s_nop 0
	v_cndmask_b32_e32 v44, v173, v44, vcc
	v_cmp_le_i32_e32 vcc, v138, v135
	v_add_u32_e32 v138, 51, v1
	s_nop 0
	v_cndmask_b32_e32 v61, v173, v61, vcc
	v_cmp_le_i32_e32 vcc, v138, v135
	v_add_u32_e32 v138, 24, v1
	s_nop 0
	v_cndmask_b32_e32 v45, v173, v45, vcc
	v_cmp_le_i32_e32 vcc, v138, v135
	v_add_u32_e32 v138, 56, v1
	s_nop 0
	v_cndmask_b32_e32 v62, v173, v62, vcc
	v_cmp_le_i32_e32 vcc, v138, v135
	v_add_u32_e32 v138, 25, v1
	s_nop 0
	v_cndmask_b32_e32 v46, v173, v46, vcc
	v_cmp_le_i32_e32 vcc, v138, v135
	v_add_u32_e32 v138, 57, v1
	s_nop 0
	v_cndmask_b32_e32 v63, v173, v63, vcc
	v_cmp_le_i32_e32 vcc, v138, v135
	v_add_u32_e32 v138, 26, v1
	s_nop 0
	v_cndmask_b32_e32 v47, v173, v47, vcc
	v_cmp_le_i32_e32 vcc, v138, v135
	v_add_u32_e32 v138, 58, v1
	s_nop 0
	v_cndmask_b32_e32 v64, v173, v64, vcc
	v_cmp_le_i32_e32 vcc, v138, v135
	v_add_u32_e32 v138, 27, v1
	v_add_u32_e32 v1, 59, v1
	v_cndmask_b32_e32 v48, v173, v48, vcc
	v_cmp_le_i32_e32 vcc, v138, v135
	s_nop 1
	v_cndmask_b32_e32 v65, v173, v65, vcc
	v_cmp_le_i32_e32 vcc, v1, v135
	s_nop 1
	v_cndmask_b32_e32 v49, v173, v49, vcc

; #define PV_STEP(OACC, mm, ktt, ss, PF) do { OACC = __builtin_amdgcn_mfma_f32_32x32x16_bf16(ldA_perm(vb + (mm) * 32 * 72 + 32 * (ktt) + 16 * (ss)), PF, OACC, 0, 0, 0); } while (0)
; __device__ __forceinline__ void attn_phase(const Ctx& c, const Params& p, int o, int first, int cidx) {
;     ...
;                 const float mnew = fmaxf(mrun, mx);
;                 if (__any(mnew > mrun)) { const float alpha = __builtin_amdgcn_exp2f(mrun - mnew); lrun *= alpha; o0 = o0 * alpha; o1 = o1 * alpha; }
;                 mrun = mnew;
;                 f32x16 e0, e1;
; #pragma unroll
;                 for (int r = 0; r < 16; ++r) { e0[r] = __builtin_amdgcn_exp2f(p0[r] - mnew); e1[r] = __builtin_amdgcn_exp2f(p1[r] - mnew); }
;                 p0 = e0; p1 = e1;
;                 { const f32x16 t = e0 + e1; lrun += ((t[0] + t[1]) + (t[2] + t[3])) + ((t[4] + t[5]) + (t[6] + t[7])) + ((t[8] + t[9]) + (t[10] + t[11])) + ((t[12] + t[13]) + (t[14] + t[15])); }
;                 const bf16x8 pf00 = pkfrag(p0, 0), pf01 = pkfrag(p0, 1), pf10 = pkfrag(p1, 0), pf11 = pkfrag(p1, 1);
;     ...
;                 PV_STEP(o0, 0, 0, 0, pf00); PV_STEP(o0, 0, 0, 1, pf01); PV_STEP(o0, 0, 1, 0, pf10); PV_STEP(o0, 0, 1, 1, pf11);
;                 PV_STEP(o1, 1, 0, 0, pf00); PV_STEP(o1, 1, 0, 1, pf01); PV_STEP(o1, 1, 1, 0, pf10); PV_STEP(o1, 1, 1, 1, pf11);
.Lsb_129b:
	v_sub_f32_e32 v38, v38, v1
	v_exp_f32_e32 v138, v38
	v_sub_f32_e32 v38, v55, v1
	v_exp_f32_e32 v55, v38
	v_sub_f32_e32 v38, v39, v1
	v_sub_f32_e32 v39, v40, v1
	v_sub_f32_e32 v40, v41, v1
	v_sub_f32_e32 v41, v42, v1
	v_sub_f32_e32 v42, v43, v1
	v_exp_f32_e32 v139, v38
	v_sub_f32_e32 v38, v56, v1
	v_exp_f32_e32 v56, v39
	v_sub_f32_e32 v39, v57, v1
	v_exp_f32_e32 v57, v40
	v_sub_f32_e32 v40, v58, v1
	v_exp_f32_e32 v58, v41
	v_sub_f32_e32 v41, v59, v1
	v_exp_f32_e32 v59, v42
	v_sub_f32_e32 v42, v60, v1
	v_exp_f32_e32 v60, v42
	v_sub_f32_e32 v42, v44, v1
	v_exp_f32_e32 v140, v42
	v_sub_f32_e32 v42, v61, v1
	v_exp_f32_e32 v61, v42
	v_sub_f32_e32 v42, v45, v1
	v_exp_f32_e32 v141, v42
	v_sub_f32_e32 v42, v62, v1
	v_exp_f32_e32 v44, v42
	v_sub_f32_e32 v42, v46, v1
	v_exp_f32_e32 v62, v42
	v_sub_f32_e32 v42, v63, v1
	v_sub_f32_e32 v50, v50, v1
	v_sub_f32_e32 v34, v34, v1
	v_sub_f32_e32 v51, v51, v1
	v_sub_f32_e32 v35, v35, v1
	v_sub_f32_e32 v52, v52, v1
	v_sub_f32_e32 v36, v36, v1
	v_sub_f32_e32 v53, v53, v1
	v_sub_f32_e32 v37, v37, v1
	v_exp_f32_e32 v45, v42
	v_sub_f32_e32 v42, v47, v1
	v_exp_f32_e32 v50, v50
	v_exp_f32_e32 v34, v34
	v_exp_f32_e32 v51, v51
	v_exp_f32_e32 v35, v35
	v_exp_f32_e32 v52, v52
	v_exp_f32_e32 v36, v36
	v_exp_f32_e32 v53, v53
	v_exp_f32_e32 v37, v37
	v_sub_f32_e32 v54, v54, v1
	v_exp_f32_e32 v63, v42
	v_sub_f32_e32 v42, v64, v1
	v_exp_f32_e32 v54, v54
	v_exp_f32_e32 v38, v38
	v_exp_f32_e32 v39, v39
	v_exp_f32_e32 v64, v42
	v_sub_f32_e32 v42, v48, v1
	v_exp_f32_e32 v142, v42
	v_sub_f32_e32 v42, v65, v1
	v_exp_f32_e32 v65, v42
	v_sub_f32_e32 v42, v49, v1
	v_exp_f32_e32 v40, v40
	v_exp_f32_e32 v41, v41
	v_exp_f32_e32 v143, v42
	v_pk_add_f32 v[184:185], v[52:53], v[36:37]
	v_pk_add_f32 v[186:187], v[50:51], v[34:35]
	v_pk_add_f32 v[170:171], v[38:39], v[56:57]
	v_pk_add_f32 v[174:175], v[54:55], v[138:139]
	v_pk_mov_b32 v[188:189], v[186:187], v[184:185] op_sel:[1,0]
	v_mov_b32_e32 v187, v185
	v_pk_add_f32 v[184:185], v[188:189], v[186:187]
	v_pk_mov_b32 v[186:187], v[174:175], v[170:171] op_sel:[1,0]
	v_mov_b32_e32 v175, v171
	v_pk_add_f32 v[170:171], v[186:187], v[174:175]
	v_pk_add_f32 v[42:43], v[64:65], v[142:143]
	v_pk_add_f32 v[46:47], v[44:45], v[62:63]
	v_pk_add_f32 v[48:49], v[60:61], v[140:141]
	v_pk_add_f32 v[168:169], v[40:41], v[58:59]
	v_pk_add_f32 v[184:185], v[184:185], v[184:185] op_sel_hi:[0,1]
	v_pk_add_f32 v[170:171], v[170:171], v[170:171] op_sel_hi:[0,1]
	v_add_f32_e32 v169, v168, v169
	v_add_f32_e32 v49, v48, v49
	v_mov_b32_e32 v168, v46
	v_mov_b32_e32 v48, v47
	v_mov_b32_e32 v184, v42
	v_mov_b32_e32 v170, v43
	s_mul_i32 s10, s18, 0x2400
	v_pk_add_f32 v[46:47], v[168:169], v[48:49]
	v_pk_add_f32 v[42:43], v[184:185], v[170:171]
	v_cvt_pk_bf16_f32 v49, v38, v39
	v_pk_add_f32 v[42:43], v[46:47], v[42:43]
	v_cvt_pk_bf16_f32 v38, v34, v35
	v_cvt_pk_bf16_f32 v34, v58, v59
	v_add_u32_e32 v58, s10, v131
	v_add_f32_e32 v42, v42, v43
	v_add_u32_e32 v59, 0x6800, v58
	v_add_f32_e32 v136, v42, v136
	v_cvt_pk_bf16_f32 v46, v50, v51
	v_cvt_pk_bf16_f32 v47, v52, v53
	v_cvt_pk_bf16_f32 v48, v54, v55
	v_cvt_pk_bf16_f32 v42, v40, v41
	v_cvt_pk_bf16_f32 v41, v56, v57
	s_waitcnt lgkmcnt(0)
	s_setprio 3
	v_mfma_f32_32x32x16_bf16 v[18:33], v[200:203], v[46:49], v[18:33]
	v_cvt_pk_bf16_f32 v43, v60, v61
	v_cvt_pk_bf16_f32 v44, v44, v45
	v_cvt_pk_bf16_f32 v45, v64, v65
	v_cvt_pk_bf16_f32 v39, v36, v37
	v_cvt_pk_bf16_f32 v40, v138, v139
	v_cvt_pk_bf16_f32 v35, v140, v141
	v_cvt_pk_bf16_f32 v36, v62, v63
	v_cvt_pk_bf16_f32 v37, v142, v143
	v_mfma_f32_32x32x16_bf16 v[2:17], v[216:219], v[46:49], v[2:17]
	v_mfma_f32_32x32x16_bf16 v[18:33], v[204:207], v[42:45], v[18:33]
	v_mfma_f32_32x32x16_bf16 v[2:17], v[220:223], v[42:45], v[2:17]
	v_mfma_f32_32x32x16_bf16 v[18:33], v[208:211], v[38:41], v[18:33]
	v_mfma_f32_32x32x16_bf16 v[2:17], v[224:227], v[38:41], v[2:17]
	v_mfma_f32_32x32x16_bf16 v[18:33], v[212:215], v[34:37], v[18:33]
	v_mfma_f32_32x32x16_bf16 v[2:17], v[228:231], v[34:37], v[2:17]
	s_setprio 1
